# v13 + MLA loop: K/V tile loads interleaved into QK MFMA cluster; loop-invariant bpermute address and LDS write addresses hoisted out of the tile loop
# speedup vs baseline: 1.0217x; 1.0217x over previous
; DI PP launder(PP p) { asm volatile("" : "+s"(p)); return p; }
; template <int DK, int MODE> ...
;     ...
;         mx = fmaxf(mx, __shfl_xor(mx, 32));
; __global__ void __launch_bounds__(256, 2) mega(Params p_unused) {
;     ...
;   for (int l = 0; l < 2; ++l) {
;     phase1(launder(p), l, smem); xcd_barrier(xb);
;     phase2(launder(p), l, smem); xcd_barrier(xb);
;     phase3(launder(p), l, 0, smem); xcd_barrier(xb);
;     phase4(launder(p), l, smem); xcd_barrier(xb);
;     phase5(launder(p), l, smem);
;     if (l == 0) xcd_barrier(xb);
;   }
.LBB0_193:
	s_or_b64 exec, exec, s[0:1]
	s_add_u32 s0, s56, 0x188
	v_writelane_b32 v215, s56, 5
	s_addc_u32 s1, s57, 0
	s_movk_i32 s72, 0xff80
	v_writelane_b32 v215, s57, 6
	v_writelane_b32 v215, s0, 7
	s_movk_i32 s74, 0xe000
	s_movk_i32 s33, 0x48
	v_writelane_b32 v215, s1, 8
	s_mov_b32 s50, 0x10000
	v_readlane_b32 s2, v215, 3
	v_readlane_b32 s3, v215, 4
	s_add_u32 s0, s2, 0x200
	s_addc_u32 s1, s3, 0
	v_writelane_b32 v215, s0, 9
	v_lshl_add_u64 v[0:1], v[0:1], 2, s[2:3]
	s_mov_b32 s51, 0x20000
	v_writelane_b32 v215, s1, 10
	s_add_u32 s0, s2, 0x1000
	s_addc_u32 s1, s3, 0
	v_writelane_b32 v215, s0, 11
	s_mov_b32 s52, 0x30000
	s_mov_b32 s53, 0xfffffc0
	v_writelane_b32 v215, s1, 12
	s_add_u32 s0, s2, 0x1100
	s_addc_u32 s1, s3, 0
	v_writelane_b32 v215, s0, 13
	s_movk_i32 s54, 0x90
	s_mov_b32 s27, 0x800000
	v_writelane_b32 v215, s1, 14
	s_add_u32 s0, s2, 0x1200
	s_addc_u32 s1, s3, 0
	v_writelane_b32 v215, s0, 15
	s_movk_i32 s55, 0x110
	v_mov_b32_e32 v190, 1
	v_writelane_b32 v215, s1, 16
	s_add_u32 s0, s2, 0x1300
	s_addc_u32 s1, s3, 0
	v_writelane_b32 v215, s0, 17
	s_cmp_eq_u32 s29, 15
	s_movk_i32 s78, 0xc0
	v_writelane_b32 v215, s1, 18
	s_cselect_b64 s[0:1], -1, 0
	v_writelane_b32 v215, s0, 19
	s_cmp_eq_u32 s29, 14
	s_mov_b32 s68, 0xf800000
	v_writelane_b32 v215, s1, 20
	s_cselect_b64 s[0:1], -1, 0
	v_writelane_b32 v215, s0, 21
	s_cmp_eq_u32 s29, 13
	v_mov_b32_e32 v191, 0x260
	v_writelane_b32 v215, s1, 22
	s_cselect_b64 s[0:1], -1, 0
	v_writelane_b32 v215, s0, 23
	s_cmp_eq_u32 s29, 12
	s_mov_b32 s69, 0x2aaaaaab
	v_writelane_b32 v215, s1, 24
	s_cselect_b64 s[0:1], -1, 0
	v_writelane_b32 v215, s0, 25
	s_cmp_eq_u32 s29, 11
	s_movk_i32 s70, 0x68
	v_writelane_b32 v215, s1, 26
	s_cselect_b64 s[0:1], -1, 0
	v_writelane_b32 v215, s0, 27
	s_cmp_eq_u32 s29, 10
	v_mbcnt_hi_u32_b32 v192, -1, v189
	v_mbcnt_hi_u32_b32 v216, -1, v189
	v_xor_b32_e32 v216, 32, v216
	v_lshlrev_b32_e32 v216, 2, v216
	v_writelane_b32 v215, s1, 28
	s_cselect_b64 s[0:1], -1, 0
	v_writelane_b32 v215, s0, 29
	s_cmp_eq_u32 s29, 9
	v_mov_b32_e32 v193, 0x3727c5ac
	v_writelane_b32 v215, s1, 30
	s_cselect_b64 s[0:1], -1, 0
	v_writelane_b32 v215, s0, 31
	s_cmp_eq_u32 s29, 8
	v_mov_b32_e32 v194, 0x42800000
	v_writelane_b32 v215, s1, 32
	s_cselect_b64 s[0:1], -1, 0
	v_writelane_b32 v215, s0, 33
	s_cmp_eq_u32 s29, 7
	v_not_b32_e32 v195, 63
	v_writelane_b32 v215, s1, 34
	s_cselect_b64 s[0:1], -1, 0
	v_writelane_b32 v215, s0, 35
	s_cmp_eq_u32 s29, 6
	v_mov_b32_e32 v196, 0x42000000
	v_writelane_b32 v215, s1, 36
	s_cselect_b64 s[0:1], -1, 0
	v_writelane_b32 v215, s0, 37
	s_cmp_eq_u32 s29, 5
	v_mov_b32_e32 v148, 0x12300
	v_writelane_b32 v215, s1, 38
	s_cselect_b64 s[0:1], -1, 0
	v_writelane_b32 v215, s0, 39
	s_cmp_eq_u32 s29, 4
	v_mov_b32_e32 v150, 0x12304
	v_writelane_b32 v215, s1, 40
	s_cselect_b64 s[0:1], -1, 0
	v_writelane_b32 v215, s0, 41
	s_cmp_eq_u32 s29, 3
	v_mov_b32_e32 v197, 0x12000
	v_writelane_b32 v215, s1, 42
	s_cselect_b64 s[0:1], -1, 0
	v_writelane_b32 v215, s0, 43
	s_cmp_eq_u32 s29, 2
	v_mov_b32_e32 v198, 0xf149f2ca
	v_writelane_b32 v215, s1, 44
	s_cselect_b64 s[0:1], -1, 0
	v_writelane_b32 v215, s0, 45
	s_cmp_eq_u32 s29, 1
	s_mov_b32 s31, 0
	v_writelane_b32 v215, s1, 46
	s_cselect_b64 s[0:1], -1, 0
	v_writelane_b32 v215, s0, 47
	s_cmp_eq_u32 s29, 0
	s_mov_b64 s[28:29], 0x1000
	v_writelane_b32 v215, s1, 48
	s_cselect_b64 s[0:1], -1, 0
	v_writelane_b32 v215, s0, 49
	s_mov_b64 s[82:83], -1
	s_mov_b64 s[34:35], 0x80
	v_writelane_b32 v215, s1, 50
	s_mov_b64 s[0:1], 0x1400
	v_lshl_add_u64 v[144:145], v[0:1], 0, s[0:1]
	s_mov_b64 s[0:1], 0x2400
	v_lshl_add_u64 v[146:147], v[0:1], 0, s[0:1]
	s_add_u32 s0, s2, 0x3400
	s_addc_u32 s1, s3, 0
	v_writelane_b32 v215, s0, 51
	v_mov_b32_e32 v1, 0
	s_mov_b64 s[36:37], 0x3000
	v_writelane_b32 v215, s1, 52
	s_add_u32 s0, s2, 0x3500
	s_addc_u32 s1, s3, 0
	v_writelane_b32 v215, s0, 53
	s_mov_b32 s73, -1
	s_mov_b32 s75, -1
	v_writelane_b32 v215, s1, 54
	s_mov_b32 s26, 0x3fb504f3
	v_readlane_b32 s2, v215, 0
	s_cmpk_lt_i32 s2, 0x910
	s_cselect_b64 s[0:1], -1, 0
	v_writelane_b32 v215, s0, 55
	s_mov_b64 s[76:77], 0x2000
	s_mov_b32 s80, 0x3a800000
	v_writelane_b32 v215, s1, 56
	s_lshr_b32 s0, s2, 3
	s_cmpk_lt_u32 s2, 0x400
	v_writelane_b32 v215, s0, 57
	s_cselect_b64 s[0:1], -1, 0
	v_writelane_b32 v215, s0, 58
	s_waitcnt lgkmcnt(0)
	s_barrier
	v_writelane_b32 v215, s1, 59
	s_and_b32 s0, s2, 7
	s_lshl_b32 s1, s2, 22
	s_lshl_b32 s66, s0, 1
	s_and_b32 s17, s1, 0x1800000
	s_cmpk_lt_i32 s2, 0x800
	s_cselect_b64 s[4:5], -1, 0
	s_cmpk_lt_i32 s2, 0x400
	v_writelane_b32 v215, s4, 60
	s_cselect_b64 s[2:3], -1, 0
	s_lshl_b32 s67, s0, 14
	s_lshl_b32 s0, s0, 20
	v_writelane_b32 v215, s5, 61
	v_writelane_b32 v214, s0, 0
	s_mov_b32 s0, 0
	v_writelane_b32 v215, s2, 62
	v_writelane_b32 v214, s0, 1
	v_writelane_b32 v214, s66, 2
	v_writelane_b32 v215, s3, 63
	s_movk_i32 s3, 0x210
	v_writelane_b32 v214, s67, 3
	s_branch .LBB0_197

; DI int get_tid() { int t = threadIdx.x; asm volatile("" : "+v"(t)); return t; }
; template <int DK, int MODE> ...
;     ...
;   const int tid = get_tid(), lane = tid & 63, wave = __builtin_amdgcn_readfirstlane(tid >> 6), l32 = lane & 31, h = lane >> 5;
;   const int tq0 = qb * 128 + 32 * wave;
;   const int qpos = tq0 + l32;
;   bf16x8 qf[NKS];
;   {
;     const bf16_t* qp = Q + (size_t)qpos * DK + h * 8;
; #pragma unroll
;     for (int ks = 0; ks < NKS; ++ks) qf[ks] = *(const bf16x8*)(qp + ks * 16);
; #pragma unroll
;     for (int ks = 0; ks < NKS; ++ks) asm volatile("" : "+v"(qf[ks]));
;   }
;   float Fref = 0.f;
;   if (MODE == 1) Fref = F[qb * 128];
;   f32x16 o0, o1;
; #pragma unroll
;   for (int e = 0; e < 16; ++e) { o0[e] = 0.f; o1[e] = 0.f; }
;   float m = -1e30f, lsum = 0.f, R = 1.f;
;     ...
;   gload(ASC ? start : ntiles - 1);
;   swrite(0);
;   __syncthreads();
.LBB0_522:
	s_and_b64 s[0:1], s[56:57], exec
	s_cselect_b32 s0, s63, s64
	s_and_b64 vcc, exec, s[48:49]
	s_mov_b64 s[4:5], -1
	s_cbranch_vccz .LBB0_541
	s_load_dwordx2 s[20:21], s[18:19], 0x110
	s_load_dwordx4 s[8:11], s[18:19], 0x100
	v_mov_b32_e32 v36, v188
	s_load_dwordx4 s[4:7], s[18:19], 0x90
	v_mov_b32_e32 v161, v1
	s_waitcnt lgkmcnt(0)
	s_add_u32 s12, s8, s52
	s_addc_u32 s13, s9, s53
	s_add_u32 s22, s10, s52
	s_addc_u32 s23, s11, s53
	s_add_u32 s8, s20, s50
	v_readfirstlane_b32 s1, v36
	s_addc_u32 s9, s21, s51
	s_ashr_i32 s1, s1, 1
	s_lshl_b32 s2, s0, 7
	s_andn2_b32 s1, s1, 31
	v_and_b32_e32 v37, 31, v36
	s_add_i32 s1, s1, s2
	v_bfe_u32 v38, v36, 5, 1
	v_or_b32_e32 v152, s1, v37
	s_waitcnt vmcnt(7)
	v_mov_b64_e32 v[2:3], s[12:13]
	v_mad_i64_i32 v[2:3], s[12:13], v152, s78, v[2:3]
	v_lshlrev_b32_e32 v0, 4, v38
	v_lshl_add_u64 v[2:3], v[2:3], 0, v[0:1]
	global_load_dwordx4 v[80:83], v[2:3], off
	global_load_dwordx4 v[128:131], v[2:3], off offset:32
	global_load_dwordx4 v[124:127], v[2:3], off offset:64
	global_load_dwordx4 v[120:123], v[2:3], off offset:96
	global_load_dwordx4 v[116:119], v[2:3], off offset:128
	global_load_dwordx4 v[112:115], v[2:3], off offset:160
	v_mul_hi_i32 v2, v36, s69
	v_lshrrev_b32_e32 v3, 31, v2
	v_ashrrev_i32_e32 v2, 1, v2
	s_waitcnt vmcnt(7)
	v_add_u32_e32 v28, 0x100, v36
	v_add_u32_e32 v39, v2, v3
	v_mul_hi_i32 v6, v28, s69
	v_mul_lo_u32 v2, v39, 12
	v_lshrrev_b32_e32 v7, 31, v6
	v_ashrrev_i32_e32 v6, 1, v6
	v_add_u32_e32 v12, 0x200, v36
	v_sub_u32_e32 v40, v36, v2
	v_add_u32_e32 v41, v6, v7
	v_mul_hi_i32 v13, v12, s69
	v_lshlrev_b32_e32 v154, 3, v40
	v_mul_lo_u32 v6, v41, 12
	v_lshrrev_b32_e32 v18, 31, v13
	v_ashrrev_i32_e32 v13, 1, v13
	v_mov_b64_e32 v[10:11], s[22:23]
	v_ashrrev_i32_e32 v155, 31, v154
	v_sub_u32_e32 v42, v28, v6
	v_add_u32_e32 v43, v13, v18
	v_mad_i64_i32 v[2:3], s[12:13], v39, s78, v[10:11]
	v_lshlrev_b64 v[14:15], 1, v[154:155]
	v_lshlrev_b32_e32 v156, 3, v42
	v_mul_lo_u32 v13, v43, 12
	v_lshl_add_u64 v[2:3], v[2:3], 0, v[14:15]
	v_ashrrev_i32_e32 v157, 31, v156
	v_sub_u32_e32 v44, v12, v13
	v_ashrrev_i32_e32 v22, 3, v36
	v_mad_i64_i32 v[6:7], s[12:13], v41, s78, v[10:11]
	v_lshlrev_b64 v[16:17], 1, v[156:157]
	v_lshlrev_b32_e32 v158, 3, v44
	v_ashrrev_i32_e32 v23, 31, v22
	v_lshl_add_u64 v[6:7], v[6:7], 0, v[16:17]
	v_ashrrev_i32_e32 v159, 31, v158
	v_lshlrev_b64 v[20:21], 14, v[22:23]
	v_lshlrev_b32_e32 v23, 3, v36
	s_waitcnt vmcnt(6)
	v_ashrrev_i32_e32 v32, 3, v28
	v_mad_i64_i32 v[10:11], s[12:13], v43, s78, v[10:11]
	v_lshlrev_b64 v[18:19], 1, v[158:159]
	v_and_b32_e32 v23, 56, v23
	v_ashrrev_i32_e32 v33, 31, v32
	v_lshl_add_u64 v[10:11], v[10:11], 0, v[18:19]
	v_lshl_add_u64 v[24:25], s[8:9], 0, v[20:21]
	v_lshlrev_b32_e32 v160, 1, v23
	v_lshlrev_b64 v[34:35], 14, v[32:33]
	v_lshl_add_u64 v[24:25], v[24:25], 0, v[160:161]
	v_lshl_add_u64 v[28:29], s[8:9], 0, v[34:35]
	v_lshl_add_u64 v[28:29], v[28:29], 0, v[160:161]
	v_mul_lo_u32 v159, v39, s70
	v_lshlrev_b32_e32 v23, 4, v40
	v_lshl_add_u32 v23, v159, 1, v23
	v_mul_lo_u32 v161, v41, s70
	s_or_b32 s8, s1, 31
	s_movk_i32 s9, 0xd0
	s_or_b32 s2, s2, 64
	v_mad_u32_u24 v175, v37, s9, v0
	s_add_u32 s9, s20, s44
	v_mul_lo_u32 v172, v43, s70
	v_lshlrev_b32_e32 v0, 6, v37
	s_addc_u32 s13, s21, s45
	v_mul_lo_u32 v173, v22, s33
	v_sub_u32_e32 v157, v175, v0
	s_waitcnt vmcnt(5)
	s_waitcnt vmcnt(4)
	s_waitcnt vmcnt(3)
	s_waitcnt vmcnt(2)
	s_waitcnt vmcnt(1)
	s_waitcnt vmcnt(0)
	global_load_dwordx4 v[2:5], v[2:3], off
	s_add_u32 s12, s9, 0x80
	global_load_dwordx4 v[6:9], v[6:7], off
	v_lshlrev_b32_e32 v0, 4, v36
	global_load_dwordx4 v[10:13], v[10:11], off
	v_mul_lo_u32 v174, v32, s33
	global_load_dwordx4 v[24:27], v[24:25], off
	s_addc_u32 s13, s13, 0
	global_load_dwordx4 v[28:31], v[28:29], off
	v_and_b32_e32 v0, 0x70, v0
	v_or_b32_e32 v34, v34, v0
	v_or_b32_e32 v20, v20, v0
	s_add_u32 s10, s10, 0x3000
	v_lshl_add_u64 v[162:163], s[12:13], 0, v[34:35]
	v_lshl_add_u64 v[164:165], s[12:13], 0, v[20:21]
	s_addc_u32 s11, s11, 0
	v_lshlrev_b32_e32 v149, 2, v38
	v_mov_b32_e32 v0, v1
	v_ashrrev_i32_e32 v153, 31, v152
	s_mov_b32 s9, 0
	v_mov_b32_e32 v155, 0xf149f2ca
	v_mov_b32_e32 v151, 0
	s_waitcnt vmcnt(4)
	ds_write_b128 v23, v[2:5]
	v_lshlrev_b32_e32 v2, 4, v42
	v_lshl_add_u32 v2, v161, 1, v2
	s_waitcnt vmcnt(3)
	ds_write_b128 v2, v[6:9]
	v_lshlrev_b32_e32 v2, 4, v44
	v_lshl_add_u32 v2, v172, 1, v2
	s_waitcnt vmcnt(2)
	ds_write_b128 v2, v[10:13]
	v_lshl_add_u32 v2, v173, 1, v160
	s_waitcnt vmcnt(1)
	ds_write_b128 v2, v[24:27] offset:26624
	v_lshl_add_u32 v2, v174, 1, v160
	s_waitcnt vmcnt(0)
	ds_write_b128 v2, v[28:31] offset:26624
	v_mad_i64_i32 v[2:3], s[12:13], v43, s78, v[18:19]
	v_lshl_add_u64 v[166:167], s[10:11], 0, v[2:3]
	v_mad_i64_i32 v[2:3], s[12:13], v41, s78, v[16:17]
	v_lshl_add_u64 v[168:169], s[10:11], 0, v[2:3]
	v_mad_i64_i32 v[2:3], s[12:13], v39, s78, v[14:15]
	v_mov_b32_e32 v14, v1
	v_mov_b32_e32 v15, v1
	v_lshl_add_u64 v[170:171], s[10:11], 0, v[2:3]
	v_mov_b32_e32 v2, v1
	v_mov_b32_e32 v3, v1
	v_mov_b32_e32 v4, v1
	v_mov_b32_e32 v5, v1
	v_mov_b32_e32 v6, v1
	v_mov_b32_e32 v7, v1
	v_mov_b32_e32 v8, v1
	v_mov_b32_e32 v9, v1
	v_mov_b32_e32 v10, v1
	v_mov_b32_e32 v11, v1
	v_mov_b32_e32 v12, v1
	v_mov_b32_e32 v13, v1
	v_mov_b64_e32 v[30:31], v[14:15]
	v_mov_b64_e32 v[46:47], v[14:15]
	s_mov_b32 s10, 0
	v_mov_b64_e32 v[28:29], v[12:13]
	v_mov_b64_e32 v[26:27], v[10:11]
	v_mov_b64_e32 v[24:25], v[8:9]
	v_mov_b64_e32 v[22:23], v[6:7]
	v_mov_b64_e32 v[20:21], v[4:5]
	v_mov_b64_e32 v[18:19], v[2:3]
	v_mov_b64_e32 v[16:17], v[0:1]
	v_mov_b64_e32 v[44:45], v[12:13]
	v_mov_b64_e32 v[42:43], v[10:11]
	v_mov_b64_e32 v[40:41], v[8:9]
	v_mov_b64_e32 v[38:39], v[6:7]
	v_mov_b64_e32 v[36:37], v[4:5]
	v_mov_b64_e32 v[34:35], v[2:3]
	v_mov_b64_e32 v[32:33], v[0:1]
	s_waitcnt lgkmcnt(0)
	s_barrier
	v_lshlrev_b32_e32 v217, 1, v159
	v_lshl_add_u32 v217, v154, 1, v217
	v_lshlrev_b32_e32 v218, 1, v161
	v_lshl_add_u32 v218, v156, 1, v218
	v_lshlrev_b32_e32 v219, 1, v172
	v_lshl_add_u32 v219, v158, 1, v219
	v_lshl_add_u32 v220, v173, 1, v160
	v_lshl_add_u32 v221, v174, 1, v160
	s_branch .LBB0_526

; template <int DK, int MODE> ...
;     ...
;   auto swrite = [&](int buf) {
; #pragma unroll
;     for (int i = 0; i < NKL; ++i) {
;       const int id = tid + 256 * i, row = id / KCH, ch = id % KCH;
;       *(u32x4*)(sK + buf * 64 * LDK + row * LDK + ch * 8) = rk[i];
;     }
; #pragma unroll
;     for (int i = 0; i < 2; ++i) {
;       const int id = tid + 256 * i, row = id >> 3, ch = id & 7;
;       *(u32x4*)(sV + buf * 64 * 72 + row * 72 + ch * 8) = rv[i];
;     }
;     if (MODE == 1) { if (tid < 64) sF[buf * 64 + tid] = Fref - rf; }
;   };
;     ...
;   for (int it = 0; it < nit; ++it) {
;     const int jt = ASC ? start + it : ntiles - 1 - it;
;     const int cur = it & 1;
;     const bool more = it + 1 < nit;
;     if (more) gload(ASC ? jt + 1 : jt - 1);
;     const int key0 = jt * 64;
;     const bool active = !CAUSAL || (key0 <= tq0 + 31);
;     if (active) {
;       f32x16 s0, s1;
;       const bf16_t* kb = sK + cur * 64 * LDK + l32 * LDK + h * 8;
;       bf16x8 kf0[NKS], kf1[NKS];
; #pragma unroll
;       for (int ks = 0; ks < NKS; ++ks) { kf0[ks] = *(const bf16x8*)(kb + ks * 16); kf1[ks] = *(const bf16x8*)(kb + 32 * LDK + ks * 16); }
;       if (MODE == 1) {
;         const float* fb = sF + cur * 64 + 4 * h;
; #pragma unroll
;         for (int g = 0; g < 4; ++g) {
;           const f32x4 f0 = *(const f32x4*)(fb + 8 * g), f1 = *(const f32x4*)(fb + 32 + 8 * g);
;           s0[4 * g] = f0.x; s0[4 * g + 1] = f0.y; s0[4 * g + 2] = f0.z; s0[4 * g + 3] = f0.w;
;           s1[4 * g] = f1.x; s1[4 * g + 1] = f1.y; s1[4 * g + 2] = f1.z; s1[4 * g + 3] = f1.w;
;         }
;       } else {
; #pragma unroll
;         for (int e = 0; e < 16; ++e) { s0[e] = 0.f; s1[e] = 0.f; }
;       }
;       __builtin_amdgcn_iglp_opt(0);
;       __builtin_amdgcn_s_setprio(1);
; #pragma unroll
;       for (int ks = 0; ks < NKS; ++ks) { s0 = MFMA(kf0[ks], qf[ks], s0); s1 = MFMA(kf1[ks], qf[ks], s1); }
;       __builtin_amdgcn_s_setprio(0);
;       const bf16_t* vb = sV + cur * 64 * 72 + l32 * 72 + h * 8;
;       bf16x8 vf0[4], vf1[4];
; #pragma unroll
;       for (int j = 0; j < 4; ++j) { vf0[j] = *(const bf16x8*)(vb + j * 16); vf1[j] = *(const bf16x8*)(vb + 32 * 72 + j * 16); }
;       __builtin_amdgcn_sched_barrier(0);
;       const bool need_mask = CAUSAL && (key0 + 63 >= tq0);
;       bf16x8 pf[4];
;       if (MODE != 2) {
;         if (need_mask) {
; #pragma unroll
.LBB0_525:
	s_xor_b32 s11, s11, 1
	s_mul_i32 s12, s11, 0x3400
	v_add_u32_e32 v0, s12, v217
	s_waitcnt vmcnt(4)
	ds_write_b128 v0, v[88:91]
	v_add_u32_e32 v0, s12, v218
	s_waitcnt vmcnt(3)
	ds_write_b128 v0, v[84:87]
	v_add_u32_e32 v0, s12, v219
	s_lshl_b32 s11, s11, 12
	s_waitcnt vmcnt(2)
	ds_write_b128 v0, v[10:13]
	s_sub_i32 s11, s12, s11
	v_add_u32_e32 v0, s11, v220
	s_waitcnt vmcnt(1)
	ds_write_b128 v0, v[6:9] offset:26624
	s_add_i32 s9, s9, 64
	s_add_i32 s10, s10, 1
	v_add_u32_e32 v0, s11, v221
	v_lshl_add_u64 v[162:163], v[162:163], 0, s[34:35]
	v_lshl_add_u64 v[164:165], v[164:165], 0, s[34:35]
	v_lshl_add_u64 v[166:167], v[166:167], 0, s[36:37]
	v_lshl_add_u64 v[168:169], v[168:169], 0, s[36:37]
	s_cmp_eq_u32 s2, s9
	v_lshl_add_u64 v[170:171], v[170:171], 0, s[36:37]
	s_waitcnt vmcnt(0)
	ds_write_b128 v0, v[2:5] offset:26624
	s_waitcnt lgkmcnt(0)
	s_barrier
	s_cbranch_scc1 .LBB0_531
.LBB0_526:
	s_and_b32 s11, s10, 1
	s_cmp_gt_i32 s9, s8
	s_cbranch_scc1 .Lmla_inactive
	s_mul_i32 s12, s11, 0x3400
	v_add_u32_e32 v0, s12, v175
	ds_read_b128 v[48:51], v0 offset:6656
	ds_read_b128 v[52:55], v0
	ds_read_b128 v[92:95], v0 offset:32
	ds_read_b128 v[96:99], v0 offset:6688
	ds_read_b128 v[100:103], v0 offset:64
	ds_read_b128 v[104:107], v0 offset:6720
	ds_read_b128 v[108:111], v0 offset:96
	ds_read_b128 v[132:135], v0 offset:6752
	ds_read_b128 v[136:139], v0 offset:128
	ds_read_b128 v[140:143], v0 offset:6784
	ds_read_b128 v[176:179], v0 offset:160
	ds_read_b128 v[180:183], v0 offset:6816
	s_setprio 1
	s_setprio 0
	s_waitcnt lgkmcnt(10)
	v_mfma_f32_32x32x16_bf16 v[64:79], v[52:55], v[80:83], 0
	s_mul_i32 s12, s11, 0x2400
	v_add_u32_e32 v0, s12, v157
	v_mfma_f32_32x32x16_bf16 v[48:63], v[48:51], v[80:83], 0
	v_lshl_add_u64 v[2:3], v[170:171], 0, s[46:47]
	global_load_dwordx4 v[88:91], v[2:3], off
	s_waitcnt lgkmcnt(9)
	v_mfma_f32_32x32x16_bf16 v[64:79], v[92:95], v[128:131], v[64:79]
	ds_read_b128 v[92:95], v0 offset:31328
	s_waitcnt lgkmcnt(9)
	v_mfma_f32_32x32x16_bf16 v[48:63], v[96:99], v[128:131], v[48:63]
	v_lshl_add_u64 v[2:3], v[168:169], 0, s[46:47]
	global_load_dwordx4 v[84:87], v[2:3], off
	ds_read_b128 v[96:99], v0 offset:26720
	s_waitcnt lgkmcnt(9)
	v_mfma_f32_32x32x16_bf16 v[64:79], v[100:103], v[124:127], v[64:79]
	ds_read_b128 v[100:103], v0 offset:26688
	s_waitcnt lgkmcnt(9)
	v_mfma_f32_32x32x16_bf16 v[48:63], v[104:107], v[124:127], v[48:63]
	v_lshl_add_u64 v[2:3], v[166:167], 0, s[46:47]
	global_load_dwordx4 v[10:13], v[2:3], off
	ds_read_b128 v[104:107], v0 offset:31296
	s_waitcnt lgkmcnt(9)
	v_mfma_f32_32x32x16_bf16 v[64:79], v[108:111], v[120:123], v[64:79]
	ds_read_b128 v[108:111], v0 offset:26656
	s_waitcnt lgkmcnt(9)
	v_mfma_f32_32x32x16_bf16 v[48:63], v[132:135], v[120:123], v[48:63]
	global_load_dwordx4 v[6:9], v[164:165], off
	ds_read_b128 v[132:135], v0 offset:31264
	s_waitcnt lgkmcnt(9)
	v_mfma_f32_32x32x16_bf16 v[64:79], v[136:139], v[116:119], v[64:79]
	ds_read_b128 v[136:139], v0 offset:26624
	s_waitcnt lgkmcnt(9)
	v_mfma_f32_32x32x16_bf16 v[48:63], v[140:143], v[116:119], v[48:63]
	s_nop 0
	global_load_dwordx4 v[2:5], v[162:163], off
	ds_read_b128 v[140:143], v0 offset:31232
	s_waitcnt lgkmcnt(9)
	v_mfma_f32_32x32x16_bf16 v[64:79], v[176:179], v[112:115], v[64:79]
	s_waitcnt lgkmcnt(8)
	v_mfma_f32_32x32x16_bf16 v[48:63], v[180:183], v[112:115], v[48:63]
	s_add_i32 s12, s9, 63
	s_cmp_lt_i32 s12, s1
	s_cbranch_scc1 .LBB0_529
	v_add_u32_e32 v0, s9, v149
	v_add_u32_e32 v14, 32, v0
	v_cmp_le_i32_e32 vcc, v14, v152
	v_add_u32_e32 v14, 33, v0
	s_nop 4
	v_cndmask_b32_e32 v48, v198, v48, vcc
	v_cmp_lt_i32_e32 vcc, v0, v152
	s_nop 1
	v_cndmask_b32_e32 v65, v198, v65, vcc
	v_cmp_le_i32_e32 vcc, v0, v152
	s_nop 1
	v_cndmask_b32_e32 v64, v198, v64, vcc
	v_cmp_le_i32_e32 vcc, v14, v152
	v_add_u32_e32 v14, 2, v0
	s_nop 0
	v_cndmask_b32_e32 v49, v198, v49, vcc
	v_cmp_le_i32_e32 vcc, v14, v152
	v_add_u32_e32 v14, 34, v0
	s_nop 0
	v_cndmask_b32_e32 v66, v198, v66, vcc
	v_cmp_le_i32_e32 vcc, v14, v152
	v_add_u32_e32 v14, 3, v0
	s_nop 0
	v_cndmask_b32_e32 v50, v198, v50, vcc
	v_cmp_le_i32_e32 vcc, v14, v152
	v_add_u32_e32 v14, 35, v0
	s_nop 0
	v_cndmask_b32_e32 v67, v198, v67, vcc
	v_cmp_le_i32_e32 vcc, v14, v152
	v_add_u32_e32 v14, 8, v0
	s_nop 0
	v_cndmask_b32_e32 v51, v198, v51, vcc
	v_cmp_le_i32_e32 vcc, v14, v152
	v_add_u32_e32 v14, 40, v0
	s_nop 0
	v_cndmask_b32_e32 v68, v198, v68, vcc
	v_cmp_le_i32_e32 vcc, v14, v152
	v_add_u32_e32 v14, 9, v0
	s_nop 0
	v_cndmask_b32_e32 v52, v198, v52, vcc
	v_cmp_le_i32_e32 vcc, v14, v152
	v_add_u32_e32 v14, 41, v0
	s_nop 0
	v_cndmask_b32_e32 v69, v198, v69, vcc
	v_cmp_le_i32_e32 vcc, v14, v152
	v_add_u32_e32 v14, 10, v0
	s_nop 0
	v_cndmask_b32_e32 v53, v198, v53, vcc
	v_cmp_le_i32_e32 vcc, v14, v152
	v_add_u32_e32 v14, 42, v0
	s_nop 0
	v_cndmask_b32_e32 v70, v198, v70, vcc
	v_cmp_le_i32_e32 vcc, v14, v152
	v_add_u32_e32 v14, 11, v0
	s_nop 0
	v_cndmask_b32_e32 v54, v198, v54, vcc
	v_cmp_le_i32_e32 vcc, v14, v152
	v_add_u32_e32 v14, 43, v0
	s_nop 0
	v_cndmask_b32_e32 v71, v198, v71, vcc
	v_cmp_le_i32_e32 vcc, v14, v152
	v_add_u32_e32 v14, 16, v0
	s_nop 0
	v_cndmask_b32_e32 v55, v198, v55, vcc
	v_cmp_le_i32_e32 vcc, v14, v152
	v_add_u32_e32 v14, 48, v0
	s_nop 0
	v_cndmask_b32_e32 v72, v198, v72, vcc
	v_cmp_le_i32_e32 vcc, v14, v152
	v_add_u32_e32 v14, 17, v0
	s_nop 0
	v_cndmask_b32_e32 v56, v198, v56, vcc
	v_cmp_le_i32_e32 vcc, v14, v152
	v_add_u32_e32 v14, 49, v0
	s_nop 0
	v_cndmask_b32_e32 v73, v198, v73, vcc
	v_cmp_le_i32_e32 vcc, v14, v152
	v_add_u32_e32 v14, 18, v0
	s_nop 0
	v_cndmask_b32_e32 v57, v198, v57, vcc
	v_cmp_le_i32_e32 vcc, v14, v152
	v_add_u32_e32 v14, 50, v0
	s_nop 0
	v_cndmask_b32_e32 v74, v198, v74, vcc
	v_cmp_le_i32_e32 vcc, v14, v152
	v_add_u32_e32 v14, 19, v0
	s_nop 0
	v_cndmask_b32_e32 v58, v198, v58, vcc
	v_cmp_le_i32_e32 vcc, v14, v152
	v_add_u32_e32 v14, 51, v0
	s_nop 0
	v_cndmask_b32_e32 v75, v198, v75, vcc
	v_cmp_le_i32_e32 vcc, v14, v152
	v_add_u32_e32 v14, 24, v0
	s_nop 0
	v_cndmask_b32_e32 v59, v198, v59, vcc
	v_cmp_le_i32_e32 vcc, v14, v152
	v_add_u32_e32 v14, 56, v0
	s_nop 0
	v_cndmask_b32_e32 v76, v198, v76, vcc
	v_cmp_le_i32_e32 vcc, v14, v152
	v_add_u32_e32 v14, 25, v0
	s_nop 0
	v_cndmask_b32_e32 v60, v198, v60, vcc
	v_cmp_le_i32_e32 vcc, v14, v152
	v_add_u32_e32 v14, 57, v0
	s_nop 0
	v_cndmask_b32_e32 v77, v198, v77, vcc
	v_cmp_le_i32_e32 vcc, v14, v152
	v_add_u32_e32 v14, 26, v0
	s_nop 0
	v_cndmask_b32_e32 v61, v198, v61, vcc
	v_cmp_le_i32_e32 vcc, v14, v152
	v_add_u32_e32 v14, 58, v0
	s_nop 0
	v_cndmask_b32_e32 v78, v198, v78, vcc
	v_cmp_le_i32_e32 vcc, v14, v152
	v_add_u32_e32 v14, 27, v0
	v_add_u32_e32 v0, 59, v0
	v_cndmask_b32_e32 v62, v198, v62, vcc
	v_cmp_le_i32_e32 vcc, v14, v152
	s_nop 1
	v_cndmask_b32_e32 v79, v198, v79, vcc
	v_cmp_le_i32_e32 vcc, v0, v152
	s_nop 1
	v_cndmask_b32_e32 v63, v198, v63, vcc
; template <int DK, int MODE> ...
;     ...
;         float mx = s0[0];
; #pragma unroll
;         for (int e = 1; e < 16; ++e) mx = fmaxf(mx, s0[e]);
; #pragma unroll
;         for (int e = 0; e < 16; ++e) mx = fmaxf(mx, s1[e]);
;         mx = fmaxf(mx, __shfl_xor(mx, 32));
;         if (__any(mx > m + 8.f)) {
;           const float mnew = fmaxf(m, mx);
;           const float alpha = __builtin_amdgcn_exp2f(m - mnew);
;           m = mnew; lsum *= alpha;
; #pragma unroll
;           for (int e = 0; e < 16; ++e) { o0[e] *= alpha; o1[e] *= alpha; }
;         }
.LBB0_529:
	s_nop 6
	v_max_f32_e32 v0, v65, v65
	v_max_f32_e32 v14, v64, v64
	v_max_f32_e32 v0, v14, v0
	v_max3_f32 v0, v0, v66, v67
	v_max3_f32 v0, v0, v68, v69
	v_max3_f32 v0, v0, v70, v71
	v_max3_f32 v0, v0, v72, v73
	v_max3_f32 v0, v0, v74, v75
	v_max3_f32 v0, v0, v76, v77
	v_max3_f32 v0, v0, v78, v79
	v_max3_f32 v0, v0, v48, v49
	v_max3_f32 v0, v0, v50, v51
	v_max3_f32 v0, v0, v52, v53
	v_max3_f32 v0, v0, v54, v55
	v_max3_f32 v0, v0, v56, v57
	v_max3_f32 v0, v0, v58, v59
	v_max3_f32 v0, v0, v60, v61
	v_max3_f32 v0, v0, v62, v63
	ds_bpermute_b32 v14, v216, v0
	s_waitcnt lgkmcnt(0)
	v_max_f32_e32 v14, v14, v14
	v_max_f32_e32 v0, v0, v14
	v_add_f32_e32 v14, 0x41000000, v155
	v_cmp_gt_f32_e32 vcc, v0, v14
	s_cbranch_vccz .LBB0_524
	v_max_f32_e32 v0, v0, v0
	v_max_f32_e32 v14, v155, v155
	v_max_f32_e32 v14, v14, v0
	v_sub_f32_e32 v0, v155, v14
	v_exp_f32_e32 v0, v0
	v_mov_b32_e32 v155, v14
	v_pk_mul_f32 v[30:31], v[30:31], v[0:1] op_sel_hi:[1,0]
	v_pk_mul_f32 v[28:29], v[28:29], v[0:1] op_sel_hi:[1,0]
	v_pk_mul_f32 v[26:27], v[26:27], v[0:1] op_sel_hi:[1,0]
	v_pk_mul_f32 v[24:25], v[24:25], v[0:1] op_sel_hi:[1,0]
	v_pk_mul_f32 v[22:23], v[22:23], v[0:1] op_sel_hi:[1,0]
	v_pk_mul_f32 v[20:21], v[20:21], v[0:1] op_sel_hi:[1,0]
	v_pk_mul_f32 v[18:19], v[18:19], v[0:1] op_sel_hi:[1,0]
	v_pk_mul_f32 v[16:17], v[16:17], v[0:1] op_sel_hi:[1,0]
	v_pk_mul_f32 v[46:47], v[46:47], v[0:1] op_sel_hi:[1,0]
	v_pk_mul_f32 v[44:45], v[44:45], v[0:1] op_sel_hi:[1,0]
	v_pk_mul_f32 v[42:43], v[42:43], v[0:1] op_sel_hi:[1,0]
	v_pk_mul_f32 v[40:41], v[40:41], v[0:1] op_sel_hi:[1,0]
	v_pk_mul_f32 v[38:39], v[38:39], v[0:1] op_sel_hi:[1,0]
	v_pk_mul_f32 v[36:37], v[36:37], v[0:1] op_sel_hi:[1,0]
	v_pk_mul_f32 v[34:35], v[34:35], v[0:1] op_sel_hi:[1,0]
	v_pk_mul_f32 v[32:33], v[32:33], v[0:1] op_sel_hi:[1,0]
	v_mul_f32_e32 v151, v151, v0
	s_branch .LBB0_524
.Lmla_inactive:
	v_lshl_add_u64 v[2:3], v[170:171], 0, s[46:47]
	global_load_dwordx4 v[88:91], v[2:3], off
	v_lshl_add_u64 v[2:3], v[168:169], 0, s[46:47]
	global_load_dwordx4 v[84:87], v[2:3], off
	v_lshl_add_u64 v[2:3], v[166:167], 0, s[46:47]
	global_load_dwordx4 v[10:13], v[2:3], off
	global_load_dwordx4 v[6:9], v[164:165], off
	s_nop 0
	global_load_dwordx4 v[2:5], v[162:163], off
	s_branch .LBB0_525

; __global__ void __launch_bounds__(256, 2) mega(Params p_unused) {
	.amdhsa_kernel _Z4mega6Params
		.amdhsa_group_segment_fixed_size 74752
		.amdhsa_private_segment_fixed_size 0
		.amdhsa_kernarg_size 648
		.amdhsa_user_sgpr_count 2
		.amdhsa_user_sgpr_dispatch_ptr 0
		.amdhsa_user_sgpr_queue_ptr 0
		.amdhsa_user_sgpr_kernarg_segment_ptr 1
		.amdhsa_user_sgpr_dispatch_id 0
		.amdhsa_user_sgpr_kernarg_preload_length 0
		.amdhsa_user_sgpr_kernarg_preload_offset 0
		.amdhsa_user_sgpr_private_segment_size 0
		.amdhsa_uses_dynamic_stack 0
		.amdhsa_enable_private_segment 0
		.amdhsa_system_sgpr_workgroup_id_x 1
		.amdhsa_system_sgpr_workgroup_id_y 0
		.amdhsa_system_sgpr_workgroup_id_z 0
		.amdhsa_system_sgpr_workgroup_info 0
		.amdhsa_system_vgpr_workitem_id 2
		.amdhsa_next_free_vgpr 224
		.amdhsa_next_free_sgpr 100
		.amdhsa_accum_offset 224
		.amdhsa_reserve_vcc 1
		.amdhsa_float_round_mode_32 0
		.amdhsa_float_round_mode_16_64 0
		.amdhsa_float_denorm_mode_32 3
		.amdhsa_float_denorm_mode_16_64 3
		.amdhsa_dx10_clamp 1
		.amdhsa_ieee_mode 1
		.amdhsa_fp16_overflow 0
		.amdhsa_tg_split 0
		.amdhsa_exception_fp_ieee_invalid_op 0
		.amdhsa_exception_fp_denorm_src 0
		.amdhsa_exception_fp_ieee_div_zero 0
		.amdhsa_exception_fp_ieee_overflow 0
		.amdhsa_exception_fp_ieee_underflow 0
		.amdhsa_exception_fp_ieee_inexact 0
		.amdhsa_exception_int_div_zero 0
	.end_amdhsa_kernel

; __global__ void __launch_bounds__(256, 2) mega(Params p_unused) {
amdhsa.kernels:
  - .agpr_count:     0
    .args:
      - .offset:         0
        .size:           392
        .value_kind:     by_value
      - .offset:         392
        .size:           4
        .value_kind:     hidden_block_count_x
      - .offset:         396
        .size:           4
        .value_kind:     hidden_block_count_y
      - .offset:         400
        .size:           4
        .value_kind:     hidden_block_count_z
      - .offset:         404
        .size:           2
        .value_kind:     hidden_group_size_x
      - .offset:         406
        .size:           2
        .value_kind:     hidden_group_size_y
      - .offset:         408
        .size:           2
        .value_kind:     hidden_group_size_z
      - .offset:         410
        .size:           2
        .value_kind:     hidden_remainder_x
      - .offset:         412
        .size:           2
        .value_kind:     hidden_remainder_y
      - .offset:         414
        .size:           2
        .value_kind:     hidden_remainder_z
      - .offset:         432
        .size:           8
        .value_kind:     hidden_global_offset_x
      - .offset:         440
        .size:           8
        .value_kind:     hidden_global_offset_y
      - .offset:         448
        .size:           8
        .value_kind:     hidden_global_offset_z
      - .offset:         456
        .size:           2
        .value_kind:     hidden_grid_dims
      - .offset:         480
        .size:           8
        .value_kind:     hidden_multigrid_sync_arg
    .group_segment_fixed_size: 74752
    .kernarg_segment_align: 8
    .kernarg_segment_size: 648
    .language:       OpenCL C
    .language_version:
      - 2
      - 0
    .max_flat_workgroup_size: 256
    .name:           _Z4mega6Params
    .private_segment_fixed_size: 0
    .sgpr_count:     106
    .sgpr_spill_count: 74
    .symbol:         _Z4mega6Params.kd
    .uniform_work_group_size: 1
    .uses_dynamic_stack: false
    .vgpr_count:     224
    .vgpr_spill_count: 0
    .wavefront_size: 64
